# attention static priority raise on waves {2,3,4,5} (the waves without extra DMA pieces on their SIMD get... mixed subset) instead of {4,5,6,7}
# baseline (speedup 1.0000x reference)
.LBB0_55:
	v_sub_u32_e64 v1, s40, v232 clamp
	s_min_u32 s30, s40, 0xe80
	s_addk_i32 s30, 0x180
	v_readfirstlane_b32 s31, v1
	s_lshr_b32 s35, s31, 6
	s_lshr_b32 s36, s30, 6
	s_and_b64 s[30:31], s[28:29], exec
	s_cselect_b32 s30, s41, s36
	s_cselect_b32 s40, 0, s35
	s_waitcnt vmcnt(0) lgkmcnt(0)
	s_barrier
	v_mov_b32_e32 v30, v0
	s_sub_i32 s41, s30, s40
	v_mov_b32_e32 v29, v0
	v_mov_b32_e32 v28, v0
	v_mov_b32_e32 v27, v0
	v_mov_b32_e32 v26, v0
	v_mov_b32_e32 v25, v0
	v_mov_b32_e32 v24, v0
	v_mov_b32_e32 v23, v0
	v_mov_b32_e32 v22, v0
	v_mov_b32_e32 v21, v0
	v_mov_b32_e32 v20, v0
	v_mov_b32_e32 v19, v0
	v_mov_b32_e32 v18, v0
	v_mov_b32_e32 v17, v0
	v_mov_b32_e32 v16, v0
	v_mov_b32_e32 v15, v0
	v_mov_b32_e32 v14, v0
	v_mov_b32_e32 v13, v0
	v_mov_b32_e32 v12, v0
	v_mov_b32_e32 v11, v0
	v_mov_b32_e32 v10, v0
	v_mov_b32_e32 v9, v0
	v_mov_b32_e32 v8, v0
	v_mov_b32_e32 v7, v0
	v_mov_b32_e32 v6, v0
	v_mov_b32_e32 v5, v0
	v_mov_b32_e32 v4, v0
	v_mov_b32_e32 v3, v0
	v_mov_b32_e32 v2, v0
	v_mov_b32_e32 v1, v0
	v_mov_b64_e32 v[62:63], v[30:31]
	s_cmp_gt_i32 s41, -4
	v_mov_b32_e32 v121, v113
	v_mov_b64_e32 v[32:33], v[0:1]
	v_mov_b64_e32 v[60:61], v[28:29]
	v_mov_b64_e32 v[58:59], v[26:27]
	v_mov_b64_e32 v[56:57], v[24:25]
	v_mov_b64_e32 v[54:55], v[22:23]
	v_mov_b64_e32 v[52:53], v[20:21]
	v_mov_b64_e32 v[50:51], v[18:19]
	v_mov_b64_e32 v[48:49], v[16:17]
	v_mov_b64_e32 v[46:47], v[14:15]
	v_mov_b64_e32 v[44:45], v[12:13]
	v_mov_b64_e32 v[42:43], v[10:11]
	v_mov_b64_e32 v[40:41], v[8:9]
	v_mov_b64_e32 v[38:39], v[6:7]
	v_mov_b64_e32 v[36:37], v[4:5]
	v_mov_b64_e32 v[34:35], v[2:3]
	s_cbranch_scc0 .LBB0_38
	s_lshl_b32 s42, s42, 12
	s_lshl_b32 s30, s43, 8
	s_add_i32 s41, s41, 4
	s_addk_i32 s42, 0xff00
	s_sub_i32 s30, 0, s30
	s_and_b64 s[28:29], s[28:29], exec
	s_cselect_b32 s28, 0xfffff000, s30
	s_lshl_b32 s29, s44, 7
	v_add_u32_e32 v123, s29, v112
	v_add_u32_e32 v125, s29, v114
	s_lshl_b32 s29, s40, 6
	s_add_i32 s29, s29, s28
	v_mov_b32_e32 v1, v0
	v_mov_b32_e32 v2, v0
	v_mov_b32_e32 v3, v0
	v_mov_b32_e32 v4, v0
	v_mov_b32_e32 v5, v0
	v_mov_b32_e32 v6, v0
	v_mov_b32_e32 v7, v0
	v_mov_b32_e32 v8, v0
	v_mov_b32_e32 v9, v0
	v_mov_b32_e32 v10, v0
	v_mov_b32_e32 v11, v0
	v_mov_b32_e32 v12, v0
	v_mov_b32_e32 v13, v0
	v_mov_b32_e32 v14, v0
	v_mov_b32_e32 v15, v0
	v_mov_b32_e32 v16, v0
	v_mov_b32_e32 v17, v0
	v_mov_b32_e32 v18, v0
	v_mov_b32_e32 v19, v0
	v_mov_b32_e32 v20, v0
	v_mov_b32_e32 v21, v0
	v_mov_b32_e32 v22, v0
	v_mov_b32_e32 v23, v0
	v_mov_b32_e32 v24, v0
	v_mov_b32_e32 v25, v0
	v_mov_b32_e32 v26, v0
	v_mov_b32_e32 v27, v0
	v_mov_b32_e32 v28, v0
	v_mov_b32_e32 v29, v0
	v_mov_b32_e32 v30, v0
	v_mov_b32_e32 v31, v0
	s_waitcnt vmcnt(0)
	v_mul_f32_e32 v131, 0x3fb8aa3b, v64
	v_sub_f32_e32 v154, 0, v131
	v_mov_b32_e32 v155, v154
	v_mov_b32_e32 v156, v154
	v_mov_b32_e32 v157, v154
	v_mov_b32_e32 v158, v154
	v_mov_b32_e32 v159, v154
	v_mov_b32_e32 v160, v154
	v_mov_b32_e32 v161, v154
	v_mov_b32_e32 v162, v154
	v_mov_b32_e32 v163, v154
	v_mov_b32_e32 v164, v154
	v_mov_b32_e32 v165, v154
	v_mov_b32_e32 v166, v154
	v_mov_b32_e32 v167, v154
	v_mov_b32_e32 v168, v154
	v_mov_b32_e32 v169, v154
	s_mov_b32 s43, 0
	v_add_u32_e32 v127, s29, v134
	s_add_i32 s44, s34, 0x80
	s_mov_b32 s45, 2
	s_mov_b32 s46, 1
	v_mov_b32_e32 v121, v113
	s_mov_b32 s48, 0
	s_mov_b32 s47, 0
	s_mul_i32 s34, s48, 0x2400
	v_add_u32_e32 v208, s34, v115
	s_mul_i32 s34, s48, 0x2400
	v_add_u32_e32 v209, s34, v133
	v_readfirstlane_b32 s30, v191
	s_lshr_b32 s30, s30, 6
	s_lshr_b32 s31, s30, 1
	s_xor_b32 s30, s30, s31
	s_bitcmp0_b32 s30, 1
	s_cbranch_scc1 .Latt_swa_p0
	s_setprio 1

.LBB0_106:
	v_mov_b32_e32 v14, v0
	v_mov_b32_e32 v15, v0
	s_waitcnt vmcnt(0) lgkmcnt(0)
	s_barrier
	v_mov_b32_e32 v1, v0
	v_mov_b32_e32 v2, v0
	v_mov_b32_e32 v3, v0
	v_mov_b32_e32 v4, v0
	v_mov_b32_e32 v5, v0
	v_mov_b32_e32 v6, v0
	v_mov_b32_e32 v7, v0
	v_mov_b32_e32 v8, v0
	v_mov_b32_e32 v9, v0
	v_mov_b32_e32 v10, v0
	v_mov_b32_e32 v11, v0
	v_mov_b32_e32 v12, v0
	v_mov_b32_e32 v13, v0
	s_lshl_b32 s30, s43, 12
	s_lshl_b32 s44, s48, 7
	v_mov_b64_e32 v[62:63], v[14:15]
	v_mov_b64_e32 v[46:47], v[14:15]
	v_mov_b64_e32 v[30:31], v[14:15]
	s_add_i32 s43, s30, 0xffffff80
	v_add_u32_e32 v153, s44, v171
	v_add_u32_e32 v155, s44, v172
	s_add_i32 s45, s46, 0x80
	s_mov_b32 s50, 2
	s_mov_b32 s51, 1
	s_mov_b32 s53, 0
	v_mov_b32_e32 v157, 0
	v_mov_b32_e32 v159, 0
	v_mov_b32_e32 v96, 0
	v_mov_b32_e32 v97, 0
	v_mov_b32_e32 v98, 0
	v_mov_b32_e32 v99, 0
	v_mov_b32_e32 v100, 0
	v_mov_b32_e32 v101, 0
	v_mov_b32_e32 v102, 0
	v_mov_b32_e32 v103, 0
	v_mov_b32_e32 v104, 0
	v_mov_b32_e32 v105, 0
	v_mov_b32_e32 v106, 0
	v_mov_b32_e32 v107, 0
	v_mov_b32_e32 v108, 0
	v_mov_b32_e32 v109, 0
	v_mov_b32_e32 v110, 0
	v_mov_b32_e32 v111, 0
	v_mov_b64_e32 v[60:61], v[12:13]
	v_mov_b64_e32 v[58:59], v[10:11]
	v_mov_b64_e32 v[56:57], v[8:9]
	v_mov_b64_e32 v[54:55], v[6:7]
	v_mov_b64_e32 v[52:53], v[4:5]
	v_mov_b64_e32 v[50:51], v[2:3]
	v_mov_b64_e32 v[48:49], v[0:1]
	v_mov_b64_e32 v[44:45], v[12:13]
	v_mov_b64_e32 v[42:43], v[10:11]
	v_mov_b64_e32 v[40:41], v[8:9]
	v_mov_b64_e32 v[38:39], v[6:7]
	v_mov_b64_e32 v[36:37], v[4:5]
	v_mov_b64_e32 v[34:35], v[2:3]
	v_mov_b64_e32 v[32:33], v[0:1]
	v_mov_b64_e32 v[28:29], v[12:13]
	v_mov_b64_e32 v[26:27], v[10:11]
	v_mov_b64_e32 v[24:25], v[8:9]
	v_mov_b64_e32 v[22:23], v[6:7]
	v_mov_b64_e32 v[20:21], v[4:5]
	v_mov_b64_e32 v[18:19], v[2:3]
	v_mov_b64_e32 v[16:17], v[0:1]
	s_mov_b32 s52, 0
	s_waitcnt vmcnt(0)
	s_mul_i32 s30, s53, 0x2400
	v_add_u32_e32 v242, s30, v173
	s_mul_i32 s30, s53, 0x4800
	v_add_u32_e32 v243, s30, v174
	v_readfirstlane_b32 s30, v191
	s_lshr_b32 s30, s30, 6
	s_lshr_b32 s31, s30, 1
	s_xor_b32 s30, s30, s31
	s_bitcmp0_b32 s30, 1
	s_cbranch_scc1 .Latt_diff_p0
	s_setprio 1

.LBB0_177:
	v_mov_b32_e32 v14, v0
	v_mov_b32_e32 v15, v0
	s_waitcnt vmcnt(0) lgkmcnt(0)
	s_barrier
	v_mov_b32_e32 v1, v0
	v_mov_b32_e32 v2, v0
	v_mov_b32_e32 v3, v0
	v_mov_b32_e32 v4, v0
	v_mov_b32_e32 v5, v0
	v_mov_b32_e32 v6, v0
	v_mov_b32_e32 v7, v0
	v_mov_b32_e32 v8, v0
	v_mov_b32_e32 v9, v0
	v_mov_b32_e32 v10, v0
	v_mov_b32_e32 v11, v0
	v_mov_b32_e32 v12, v0
	v_mov_b32_e32 v13, v0
	s_lshl_b32 s49, s49, 12
	v_mov_b64_e32 v[30:31], v[14:15]
	v_mov_b64_e32 v[46:47], v[14:15]
	v_mov_b64_e32 v[62:63], v[14:15]
	v_mad_u64_u32 v[222:223], s[30:31], s50, v238, v[190:191]
	v_mad_u64_u32 v[224:225], s[30:31], s50, v240, v[192:193]
	v_mad_u64_u32 v[226:227], s[30:31], s50, v242, v[194:195]
	v_mad_u64_u32 v[228:229], s[30:31], s50, v244, v[196:197]
	s_addk_i32 s49, 0xff80
	s_add_i32 s51, s60, 0x80
	s_mov_b32 s52, 2
	s_mov_b32 s53, 1
	s_mov_b32 s56, 0
	v_mov_b32_e32 v205, 0
	v_mov_b32_e32 v207, 0
	v_mov_b32_e32 v96, 0
	v_mov_b32_e32 v97, 0
	v_mov_b32_e32 v98, 0
	v_mov_b32_e32 v99, 0
	v_mov_b32_e32 v100, 0
	v_mov_b32_e32 v101, 0
	v_mov_b32_e32 v102, 0
	v_mov_b32_e32 v103, 0
	v_mov_b32_e32 v104, 0
	v_mov_b32_e32 v105, 0
	v_mov_b32_e32 v106, 0
	v_mov_b32_e32 v107, 0
	v_mov_b32_e32 v108, 0
	v_mov_b32_e32 v109, 0
	v_mov_b32_e32 v110, 0
	v_mov_b32_e32 v111, 0
	v_mov_b64_e32 v[28:29], v[12:13]
	v_mov_b64_e32 v[26:27], v[10:11]
	v_mov_b64_e32 v[24:25], v[8:9]
	v_mov_b64_e32 v[22:23], v[6:7]
	v_mov_b64_e32 v[20:21], v[4:5]
	v_mov_b64_e32 v[18:19], v[2:3]
	v_mov_b64_e32 v[16:17], v[0:1]
	v_mov_b64_e32 v[44:45], v[12:13]
	v_mov_b64_e32 v[42:43], v[10:11]
	v_mov_b64_e32 v[40:41], v[8:9]
	v_mov_b64_e32 v[38:39], v[6:7]
	v_mov_b64_e32 v[36:37], v[4:5]
	v_mov_b64_e32 v[34:35], v[2:3]
	v_mov_b64_e32 v[32:33], v[0:1]
	v_mov_b64_e32 v[60:61], v[12:13]
	v_mov_b64_e32 v[58:59], v[10:11]
	v_mov_b64_e32 v[56:57], v[8:9]
	v_mov_b64_e32 v[54:55], v[6:7]
	v_mov_b64_e32 v[52:53], v[4:5]
	v_mov_b64_e32 v[50:51], v[2:3]
	v_mov_b64_e32 v[48:49], v[0:1]
	s_mov_b32 s55, 0
	s_waitcnt vmcnt(0)
	s_mul_i32 s30, s56, 0x6400
	v_add_u32_e32 v209, s30, v246
	s_mul_i32 s30, s56, 0x4800
	v_add_u32_e32 v219, s30, v247
	v_readfirstlane_b32 s30, v191
	s_lshr_b32 s30, s30, 6
	s_lshr_b32 s31, s30, 1
	s_xor_b32 s30, s30, s31
	s_bitcmp0_b32 s30, 1
	s_cbranch_scc1 .Latt_mla_p0
	s_setprio 1
